# T9 + gather sort stage: row-scale and gate gathers issued together (one round trip per token instead of three)
# speedup vs baseline: 1.0005x; 1.0005x over previous
; __device__ __forceinline__ void peer_gather_f4p(const float* X, const int* __restrict__ IDX, const float* __restrict__ G, ...
;     ...
;         keys[kt * 128 + lane] = k0; keys[kt * 128 + 64 + lane] = k1;
;         sub[kt * 128 + lane] = SU[k0 >> 7]; sub[kt * 128 + 64 + lane] = SU[k1 >> 7];
;         wbuf[kt * 128 + lane] = G[(size_t)row * 128 + (k0 & 127)] * SV[k0 >> 7]; wbuf[kt * 128 + 64 + lane] = G[(size_t)row * 128 + (k1 & 127)] * SV[k1 >> 7];
.LBB0_527:
	v_add_u32_e32 v4, s15, v4
	s_waitcnt lgkmcnt(0)
	v_min_i32_e32 v7, v5, v6
	v_max_i32_e32 v5, v5, v6
	v_lshl_add_u32 v11, v4, 2, s14
	v_ashrrev_i32_e32 v4, 7, v2
	v_cndmask_b32_e32 v10, v5, v7, vcc
	v_ashrrev_i32_e32 v5, 31, v4
	v_lshlrev_b64 v[4:5], 2, v[4:5]
	v_lshl_add_u64 v[6:7], s[40:41], 0, v[4:5]
	v_lshl_add_u64 v[4:5], s[56:57], 0, v[4:5]
	flat_load_dword v12, v[6:7]
	ds_write2st64_b32 v11, v2, v10 offset1:1
	flat_load_dword v214, v[4:5]
	v_ashrrev_i32_e32 v6, 7, v10
	v_ashrrev_i32_e32 v7, 31, v6
	v_lshlrev_b64 v[6:7], 2, v[6:7]
	v_lshl_add_u64 v[8:9], s[40:41], 0, v[6:7]
	flat_load_dword v215, v[8:9]
	v_lshl_add_u64 v[8:9], s[56:57], 0, v[6:7]
	flat_load_dword v216, v[8:9]
	v_and_b32_e32 v2, 0x7f, v2
	s_add_u32 s16, s12, s52
	v_lshlrev_b32_e32 v2, 2, v2
	s_addc_u32 s17, s13, s53
	s_mov_b32 s18, 0x27450000
	s_add_u32 s52, s52, 0x200
	s_addc_u32 s53, s53, 0
	s_addk_i32 s15, 0x80
	v_lshl_add_u64 v[8:9], s[16:17], 0, v[2:3]
	v_add_co_u32_e32 v8, vcc, s18, v8
	s_nop 1
	v_addc_co_u32_e32 v9, vcc, 0, v9, vcc
	flat_load_dword v217, v[8:9]
	v_and_b32_e32 v2, 0x7f, v10
	v_lshlrev_b32_e32 v2, 2, v2
	v_lshl_add_u64 v[4:5], s[16:17], 0, v[2:3]
	v_add_co_u32_e32 v4, vcc, s18, v4
	s_nop 1
	v_addc_co_u32_e32 v5, vcc, 0, v5, vcc
	flat_load_dword v218, v[4:5]
	s_cmpk_eq_i32 s52, 0x800
	s_waitcnt vmcnt(0) lgkmcnt(0)
	ds_write2st64_b32 v11, v12, v215 offset0:8 offset1:9
	v_mul_f32_e32 v8, v217, v214
	v_mul_f32_e32 v2, v218, v216
	ds_write2st64_b32 v11, v8, v2 offset0:16 offset1:17
	s_cbranch_scc1 .LBB0_530

; __device__ __forceinline__ void peer_gather_f4p(const float* X, const int* __restrict__ IDX, const float* __restrict__ G, ...
;     ...
;         keys[kt * 128 + lane] = k0; keys[kt * 128 + 64 + lane] = k1;
;         sub[kt * 128 + lane] = SU[k0 >> 7]; sub[kt * 128 + 64 + lane] = SU[k1 >> 7];
;         wbuf[kt * 128 + lane] = G[(size_t)row * 128 + (k0 & 127)] * SV[k0 >> 7]; wbuf[kt * 128 + 64 + lane] = G[(size_t)row * 128 + (k1 & 127)] * SV[k1 >> 7];
.LBB0_1224:
	v_add_u32_e32 v4, s15, v4
	s_waitcnt lgkmcnt(0)
	v_min_i32_e32 v7, v5, v6
	v_max_i32_e32 v5, v5, v6
	v_lshl_add_u32 v11, v4, 2, s14
	v_ashrrev_i32_e32 v4, 7, v2
	v_cndmask_b32_e32 v10, v5, v7, vcc
	v_ashrrev_i32_e32 v5, 31, v4
	v_lshlrev_b64 v[4:5], 2, v[4:5]
	v_lshl_add_u64 v[6:7], s[56:57], 0, v[4:5]
	v_lshl_add_u64 v[4:5], s[54:55], 0, v[4:5]
	flat_load_dword v12, v[6:7]
	ds_write2st64_b32 v11, v2, v10 offset1:1
	flat_load_dword v214, v[4:5]
	v_ashrrev_i32_e32 v6, 7, v10
	v_ashrrev_i32_e32 v7, 31, v6
	v_lshlrev_b64 v[6:7], 2, v[6:7]
	v_lshl_add_u64 v[8:9], s[56:57], 0, v[6:7]
	flat_load_dword v215, v[8:9]
	v_lshl_add_u64 v[8:9], s[54:55], 0, v[6:7]
	flat_load_dword v216, v[8:9]
	v_and_b32_e32 v2, 0x7f, v2
	s_add_u32 s16, s12, s52
	v_lshlrev_b32_e32 v2, 2, v2
	s_addc_u32 s17, s13, s53
	s_mov_b32 s18, 0x27450000
	s_add_u32 s52, s52, 0x200
	s_addc_u32 s53, s53, 0
	s_addk_i32 s15, 0x80
	v_lshl_add_u64 v[8:9], s[16:17], 0, v[2:3]
	v_add_co_u32_e32 v8, vcc, s18, v8
	s_nop 1
	v_addc_co_u32_e32 v9, vcc, 0, v9, vcc
	flat_load_dword v217, v[8:9]
	v_and_b32_e32 v2, 0x7f, v10
	v_lshlrev_b32_e32 v2, 2, v2
	v_lshl_add_u64 v[4:5], s[16:17], 0, v[2:3]
	v_add_co_u32_e32 v4, vcc, s18, v4
	s_nop 1
	v_addc_co_u32_e32 v5, vcc, 0, v5, vcc
	flat_load_dword v218, v[4:5]
	s_cmpk_eq_i32 s52, 0x800
	s_waitcnt vmcnt(0) lgkmcnt(0)
	ds_write2st64_b32 v11, v12, v215 offset0:8 offset1:9
	v_mul_f32_e32 v8, v217, v214
	v_mul_f32_e32 v2, v218, v216
	ds_write2st64_b32 v11, v8, v2 offset0:16 offset1:17
	s_cbranch_scc1 .LBB0_1227
